# GU layer-0 GEMM main loop: 4-slot ring of K=32 half-stages with SGPR-base (saddr) LDS-DMA addressing
# baseline (speedup 1.0000x reference)
.LBB0_591:
	v_readlane_b32 s8, v239, 43
	v_and_b32_e32 v2, 31, v194
	s_and_b32 s31, s8, 0xc0
	s_lshl_b32 s0, s62, 5
	v_or_b32_e32 v0, s31, v2
	s_and_b32 s33, s0, 0x7fffff80
	s_lshl_b32 s34, s62, 10
	v_lshlrev_b32_e32 v195, 7, v0
	v_or_b32_e32 v0, s33, v2
	s_cmpk_lt_u32 s8, 0x100
	v_lshlrev_b32_e32 v196, 7, v0
	v_lshrrev_b32_e32 v0, 4, v194
	s_cselect_b64 s[0:1], -1, 0
	s_cmpk_gt_u32 s8, 0xff
	v_lshl_add_u32 v0, s62, 2, v0
	s_cselect_b64 s[6:7], -1, 0
	s_andn2_b32 s8, s8, 63
	v_xor_b32_e32 v6, v0, v194
	v_add_u32_e32 v0, s8, v194
	v_ashrrev_i32_e32 v197, 3, v0
	v_lshl_add_u32 v0, s3, 8, v197
	v_ashrrev_i32_e32 v1, 31, v0
	v_readlane_b32 s44, v239, 32
	v_lshlrev_b64 v[0:1], 11, v[0:1]
	v_readlane_b32 s45, v239, 33
	v_lshlrev_b32_e32 v6, 4, v6
	v_and_b32_e32 v176, 0x70, v6
	v_lshl_add_u64 v[0:1], s[44:45], 0, v[0:1]
	v_mov_b32_e32 v177, 0
	v_lshl_add_u64 v[190:191], v[0:1], 0, v[176:177]
	v_lshl_add_u32 v0, s2, 8, v197
	v_ashrrev_i32_e32 v1, 31, v0
	v_lshlrev_b64 v[0:1], 11, v[0:1]
	v_lshl_add_u64 v[0:1], s[16:17], 0, v[0:1]
	s_mov_b32 m0, s34
	s_mov_b64 s[8:9], 0x20000
	s_add_i32 s35, s34, 0x2000
	v_lshl_add_u64 v[192:193], v[0:1], 0, v[176:177]
	s_waitcnt lgkmcnt(0)
	s_barrier
	global_load_lds_dwordx4 v[190:191], off
	v_lshl_add_u64 v[0:1], v[190:191], 0, s[8:9]
	s_mov_b32 m0, s35
	s_mov_b64 s[12:13], 0x40000
	s_add_i32 s36, s34, 0x4000
	global_load_lds_dwordx4 v[0:1], off
	v_lshl_add_u64 v[0:1], v[190:191], 0, s[12:13]
	s_mov_b32 m0, s36
	s_mov_b64 s[22:23], 0x60000
	s_add_i32 s37, s34, 0x6000
	global_load_lds_dwordx4 v[0:1], off
	v_lshl_add_u64 v[0:1], v[190:191], 0, s[22:23]
	s_mov_b32 m0, s37
	s_add_i32 s38, s34, 0x8000
	global_load_lds_dwordx4 v[0:1], off
	s_mov_b32 m0, s38
	s_add_i32 s39, s34, 0xa000
	global_load_lds_dwordx4 v[192:193], off
	v_lshl_add_u64 v[0:1], v[192:193], 0, s[8:9]
	s_mov_b32 m0, s39
	s_add_i32 s40, s34, 0xc000
	global_load_lds_dwordx4 v[0:1], off
	v_lshl_add_u64 v[0:1], v[192:193], 0, s[12:13]
	s_mov_b32 m0, s40
	s_add_i32 s41, s34, 0xe000
	global_load_lds_dwordx4 v[0:1], off
	v_lshl_add_u64 v[0:1], v[192:193], 0, s[22:23]
	s_mov_b32 m0, s41
	v_lshrrev_b32_e32 v3, 1, v194
	global_load_lds_dwordx4 v[0:1], off
	v_lshrrev_b32_e32 v7, 5, v194
	v_bitop3_b32 v0, v3, v7, 7 bitop3:0x6c
	v_lshlrev_b32_e32 v198, 4, v0
	v_add_u32_e32 v0, 2, v7
	v_bfe_u32 v4, v194, 1, 3
	v_bitop3_b32 v0, v0, v3, 7 bitop3:0x78
	v_lshrrev_b32_e32 v9, 3, v194
	v_lshlrev_b32_e32 v199, 4, v0
	v_bitop3_b32 v0, v7, v4, 4 bitop3:0x36
	v_mul_u32_u24_e32 v10, 0x88, v9
	v_mul_hi_u32_u24_e32 v183, 0x1600, v9
	v_mul_u32_u24_e32 v182, 0x1600, v9
	v_add_u32_e32 v9, 64, v194
	v_lshlrev_b32_e32 v200, 4, v0
	v_add_u32_e32 v0, 6, v7
	s_bfe_u32 s2, s10, 0x10003
	v_lshrrev_b32_e32 v9, 3, v9
	v_bitop3_b32 v0, v0, v3, 7 bitop3:0x78
	s_or_b32 s42, s2, 20
	s_lshl_b32 s2, s62, 13
	v_mul_u32_u24_e32 v11, 0x88, v9
	v_mul_hi_u32_u24_e32 v185, 0x1600, v9
	v_mul_u32_u24_e32 v184, 0x1600, v9
	v_or_b32_e32 v9, 0x80, v194
	v_lshlrev_b32_e32 v201, 4, v0
	s_add_i32 s2, s2, 0x10000
	v_mul_u32_u24_e32 v0, 0x88, v2
	v_lshrrev_b32_e32 v9, 3, v9
	v_or_b32_e32 v2, s2, v0
	v_lshrrev_b32_e32 v0, 2, v194
	v_mul_u32_u24_e32 v12, 0x88, v9
	v_mul_hi_u32_u24_e32 v187, 0x1600, v9
	v_mul_u32_u24_e32 v186, 0x1600, v9
	v_add_u32_e32 v9, 0xc0, v194
	s_waitcnt vmcnt(0)
	v_and_b32_e32 v7, 24, v0
	v_and_b32_e32 v0, 7, v194
	v_lshrrev_b32_e32 v9, 3, v9
	v_add_u32_e32 v5, 0x8000, v196
	v_readlane_b32 s46, v239, 34
	v_readlane_b32 s47, v239, 35
	v_readlane_b32 s48, v239, 36
	v_readlane_b32 s49, v239, 37
	v_readlane_b32 s50, v239, 38
	v_readlane_b32 s51, v239, 39
	v_or_b32_e32 v1, 0x10000, v198
	v_or_b32_e32 v3, 0x10000, v199
	v_or_b32_e32 v4, 0x10000, v200
	v_or_b32_e32 v6, 0x10000, v201
	v_lshl_or_b32 v8, v0, 4, s2
	v_lshlrev_b32_e32 v0, 3, v0
	v_mul_u32_u24_e32 v13, 0x88, v9
	v_mul_hi_u32_u24_e32 v189, 0x1600, v9
	v_mul_u32_u24_e32 v188, 0x1600, v9
	v_cndmask_b32_e64 v9, 0, 1, s[0:1]
	v_lshl_add_u64 v[178:179], s[44:45], 0, v[176:177]
	v_lshl_add_u64 v[180:181], s[16:17], 0, v[176:177]
	s_lshr_b32 s43, s10, 4
	s_lshr_b32 s44, s10, 5
	s_bfe_u32 s45, s10, 0x20003
	v_or_b32_e32 v202, 0x10000, v195
	v_add_u32_e32 v203, 0x18000, v196
	s_mov_b32 s24, 64
	s_mov_b32 s46, 0
	v_add_u32_e32 v204, v196, v198
	v_add_u32_e32 v205, v195, v198
	v_cmp_ne_u32_e64 s[0:1], 1, v9
	s_add_i32 s47, s34, 0x10000
	s_add_i32 s48, s34, 0x12000
	s_add_i32 s49, s34, 0x14000
	s_add_i32 s50, s34, 0x16000
	s_add_i32 s51, s34, 0x18000
	s_add_i32 s52, s34, 0x1a000
	s_add_i32 s53, s34, 0x1c000
	s_add_i32 s54, s34, 0x1e000
	v_add_u32_e32 v206, v1, v5
	v_add_u32_e32 v207, v3, v5
	v_add_u32_e32 v208, v4, v5
	v_add_u32_e32 v209, v6, v5
	v_lshlrev_b32_e32 v176, 1, v0
	v_add_u32_e32 v210, v2, v7
	v_add_u32_e32 v211, v8, v10
	v_add_u32_e32 v212, v8, v11
	v_add_u32_e32 v213, v8, v12
	v_add_u32_e32 v214, v8, v13
	s_mov_b32 s55, 0
	s_waitcnt vmcnt(0) lgkmcnt(0)
	s_barrier
	v_mbcnt_lo_u32_b32 v252, -1, 0
	v_mbcnt_hi_u32_b32 v252, -1, v252
	v_readlane_b32 s101, v239, 60
	v_lshrrev_b32_e32 v253, 2, v252
	v_lshrrev_b32_e32 v254, 4, v252
	v_xor_b32_e32 v254, v254, v252
	v_and_b32_e32 v254, 3, v254
	v_lshl_add_u32 v253, s101, 4, v253
	v_lshlrev_b32_e32 v253, 11, v253
	v_lshl_add_u32 v253, v254, 4, v253
	v_and_b32_e32 v254, 0xffffff80, v178
	v_add_co_u32_e32 v248, vcc, v254, v253
	s_nop 1
	v_addc_co_u32_e32 v249, vcc, 0, v179, vcc
	v_and_b32_e32 v254, 0xffffff80, v180
	v_add_co_u32_e32 v250, vcc, v254, v253
	s_nop 1
	v_addc_co_u32_e32 v251, vcc, 0, v181, vcc
	v_and_b32_e32 v253, 31, v252
	v_lshrrev_b32_e32 v254, 5, v252
	v_bfe_u32 v255, v252, 2, 2
	v_xor_b32_e32 v254, v254, v255
	v_lshlrev_b32_e32 v254, 4, v254
	v_lshl_or_b32 v254, v253, 6, v254
	s_and_b32 vcc_lo, s101, 3
	s_lshl_b32 vcc_lo, vcc_lo, 12
	v_add_u32_e32 v240, vcc_lo, v254
	s_lshr_b32 vcc_lo, s101, 2
	s_lshl_b32 vcc_lo, vcc_lo, 13
	s_add_u32 vcc_lo, vcc_lo, 0x4000
	v_add_u32_e32 v242, vcc_lo, v254
	v_xor_b32_e32 v241, 32, v240
	v_xor_b32_e32 v243, 32, v242
	v_add_u32_e32 v244, 0x10000, v240
	v_add_u32_e32 v245, 0x10000, v241
	v_add_u32_e32 v246, 0x10000, v242
	v_add_u32_e32 v247, 0x10000, v243
	s_lshl_b32 s101, s101, 10
	s_mov_b32 vcc_lo, 0
	v_and_b32_e32 v254, 0xffffff80, v178
	s_nop 1
	v_readfirstlane_b32 s56, v254
	v_readfirstlane_b32 s57, v179
	v_and_b32_e32 v255, 0xffffff80, v180
	s_nop 1
	v_readfirstlane_b32 s58, v255
	v_readfirstlane_b32 s59, v181
	v_and_b32_e32 v254, 0xffffff80, v178
	v_sub_u32_e32 v248, v248, v254
	s_lshl_b32 vcc_lo, vcc_lo, 3
	s_and_b32 vcc_hi, s10, 7
	s_add_u32 vcc_lo, vcc_lo, vcc_hi
	s_lshr_b32 s99, s10, 3
	s_cmp_lt_u32 vcc_lo, 90
	s_cbranch_scc0 .Lrg_gu2_2
	s_mul_i32 vcc_hi, vcc_lo, 0xcccd
	s_lshr_b32 vcc_hi, vcc_hi, 18
	s_mul_i32 m0, vcc_hi, 5
	s_sub_u32 m0, vcc_lo, m0
	s_lshl_b32 vcc_hi, vcc_hi, 3
	s_lshr_b32 vcc_lo, s99, 2
	s_add_u32 vcc_lo, vcc_lo, vcc_hi
	s_and_b32 vcc_hi, s99, 3
	s_lshl_b32 m0, m0, 2
	s_add_u32 vcc_hi, vcc_hi, m0
	s_branch .Lrg_gud_2
.Lrg_gu2_2:
	s_sub_u32 vcc_lo, vcc_lo, 90
	s_lshl_b32 vcc_lo, vcc_lo, 4
	s_lshr_b32 vcc_hi, s99, 1
	s_add_u32 vcc_lo, vcc_lo, vcc_hi
	s_and_b32 vcc_hi, s99, 1
	s_add_u32 vcc_hi, vcc_hi, 20
.Lrg_gud_2:
	s_lshl_b32 s99, vcc_lo, 19
	s_lshl_b32 s100, vcc_hi, 19
	s_mov_b32 vcc_hi, 0
	s_add_u32 vcc_lo, s99, 0
	v_add_u32_e32 v252, vcc_lo, v248
	s_add_u32 m0, s101, 0
	v_add_u32_e32 v253, 262144, v252
	global_load_lds_dwordx4 v252, s[56:57]
	s_add_u32 m0, s101, 8192
	s_add_u32 vcc_lo, s100, 0
	global_load_lds_dwordx4 v253, s[56:57]
	v_add_u32_e32 v254, vcc_lo, v248
	s_add_u32 m0, s101, 16384
	v_add_u32_e32 v255, 262144, v254
	global_load_lds_dwordx4 v254, s[58:59]
	s_add_u32 m0, s101, 24576
	s_nop 0
	global_load_lds_dwordx4 v255, s[58:59]
	s_add_u32 vcc_lo, s99, 64
	v_add_u32_e32 v252, vcc_lo, v248
	s_add_u32 m0, s101, 32768
	v_add_u32_e32 v253, 262144, v252
	global_load_lds_dwordx4 v252, s[56:57]
	s_add_u32 m0, s101, 40960
	s_add_u32 vcc_lo, s100, 64
	global_load_lds_dwordx4 v253, s[56:57]
	v_add_u32_e32 v254, vcc_lo, v248
	s_add_u32 m0, s101, 49152
	v_add_u32_e32 v255, 262144, v254
	global_load_lds_dwordx4 v254, s[58:59]
	s_add_u32 m0, s101, 57344
	s_nop 0
	global_load_lds_dwordx4 v255, s[58:59]
	s_waitcnt vmcnt(4)
	s_barrier
	s_branch .LBB0_593

.LBB0_593:
	s_mov_b32 s66, -2
	s_mov_b32 vcc_hi, 0
	s_add_u32 vcc_lo, s99, 128
	v_add_u32_e32 v252, vcc_lo, v248
	s_add_u32 m0, s101, 65536
	v_add_u32_e32 v253, 262144, v252
	global_load_lds_dwordx4 v252, s[56:57]
	s_add_u32 m0, s101, 73728
	s_add_u32 vcc_lo, s100, 128
	global_load_lds_dwordx4 v253, s[56:57]
	v_add_u32_e32 v254, vcc_lo, v248
	s_add_u32 m0, s101, 81920
	v_add_u32_e32 v255, 262144, v254
	global_load_lds_dwordx4 v254, s[58:59]
	s_add_u32 m0, s101, 90112
	s_nop 0
	global_load_lds_dwordx4 v255, s[58:59]
	v_mov_b32_e32 v0, 0
	v_mov_b32_e32 v1, 0
	v_mov_b32_e32 v2, 0
	v_mov_b32_e32 v3, 0
	v_mov_b32_e32 v4, 0
	v_mov_b32_e32 v5, 0
	v_mov_b32_e32 v6, 0
	v_mov_b32_e32 v7, 0
	v_mov_b32_e32 v8, 0
	v_mov_b32_e32 v9, 0
	v_mov_b32_e32 v10, 0
	v_mov_b32_e32 v11, 0
	v_mov_b32_e32 v12, 0
	v_mov_b32_e32 v13, 0
	v_mov_b32_e32 v14, 0
	v_mov_b32_e32 v15, 0
	v_mov_b32_e32 v16, 0
	v_mov_b32_e32 v17, 0
	v_mov_b32_e32 v18, 0
	v_mov_b32_e32 v19, 0
	v_mov_b32_e32 v20, 0
	v_mov_b32_e32 v21, 0
	v_mov_b32_e32 v22, 0
	v_mov_b32_e32 v23, 0
	v_mov_b32_e32 v24, 0
	v_mov_b32_e32 v25, 0
	v_mov_b32_e32 v26, 0
	v_mov_b32_e32 v27, 0
	v_mov_b32_e32 v28, 0
	v_mov_b32_e32 v29, 0
	v_mov_b32_e32 v30, 0
	v_mov_b32_e32 v31, 0
	v_mov_b32_e32 v32, 0
	v_mov_b32_e32 v33, 0
	v_mov_b32_e32 v34, 0
	v_mov_b32_e32 v35, 0
	v_mov_b32_e32 v36, 0
	v_mov_b32_e32 v37, 0
	v_mov_b32_e32 v38, 0
	v_mov_b32_e32 v39, 0
	v_mov_b32_e32 v40, 0
	v_mov_b32_e32 v41, 0
	v_mov_b32_e32 v42, 0
	v_mov_b32_e32 v43, 0
	v_mov_b32_e32 v44, 0
	v_mov_b32_e32 v45, 0
	v_mov_b32_e32 v46, 0
	v_mov_b32_e32 v47, 0
	v_mov_b32_e32 v48, 0
	v_mov_b32_e32 v49, 0
	v_mov_b32_e32 v50, 0
	v_mov_b32_e32 v51, 0
	v_mov_b32_e32 v52, 0
	v_mov_b32_e32 v53, 0
	v_mov_b32_e32 v54, 0
	v_mov_b32_e32 v55, 0
	v_mov_b32_e32 v56, 0
	v_mov_b32_e32 v57, 0
	v_mov_b32_e32 v58, 0
	v_mov_b32_e32 v59, 0
	v_mov_b32_e32 v60, 0
	v_mov_b32_e32 v61, 0
	v_mov_b32_e32 v62, 0
	v_mov_b32_e32 v63, 0
	v_mov_b32_e32 v64, 0
	v_mov_b32_e32 v65, 0
	v_mov_b32_e32 v66, 0
	v_mov_b32_e32 v67, 0
	v_mov_b32_e32 v68, 0
	v_mov_b32_e32 v69, 0
	v_mov_b32_e32 v70, 0
	v_mov_b32_e32 v71, 0
	v_mov_b32_e32 v72, 0
	v_mov_b32_e32 v73, 0
	v_mov_b32_e32 v74, 0
	v_mov_b32_e32 v75, 0
	v_mov_b32_e32 v76, 0
	v_mov_b32_e32 v77, 0
	v_mov_b32_e32 v78, 0
	v_mov_b32_e32 v79, 0
	v_mov_b32_e32 v80, 0
	v_mov_b32_e32 v81, 0
	v_mov_b32_e32 v82, 0
	v_mov_b32_e32 v83, 0
	v_mov_b32_e32 v84, 0
	v_mov_b32_e32 v85, 0
	v_mov_b32_e32 v86, 0
	v_mov_b32_e32 v87, 0
	v_mov_b32_e32 v88, 0
	v_mov_b32_e32 v89, 0
	v_mov_b32_e32 v90, 0
	v_mov_b32_e32 v91, 0
	v_mov_b32_e32 v92, 0
	v_mov_b32_e32 v93, 0
	v_mov_b32_e32 v94, 0
	v_mov_b32_e32 v95, 0
	v_mov_b32_e32 v96, 0
	v_mov_b32_e32 v97, 0
	v_mov_b32_e32 v98, 0
	v_mov_b32_e32 v99, 0
	v_mov_b32_e32 v100, 0
	v_mov_b32_e32 v101, 0
	v_mov_b32_e32 v102, 0
	v_mov_b32_e32 v103, 0
	v_mov_b32_e32 v104, 0
	v_mov_b32_e32 v105, 0
	v_mov_b32_e32 v106, 0
	v_mov_b32_e32 v107, 0
	v_mov_b32_e32 v108, 0
	v_mov_b32_e32 v109, 0
	v_mov_b32_e32 v110, 0
	v_mov_b32_e32 v111, 0
	v_mov_b32_e32 v112, 0
	v_mov_b32_e32 v113, 0
	v_mov_b32_e32 v114, 0
	v_mov_b32_e32 v115, 0
	v_mov_b32_e32 v116, 0
	v_mov_b32_e32 v117, 0
	v_mov_b32_e32 v118, 0
	v_mov_b32_e32 v119, 0
	v_mov_b32_e32 v120, 0
	v_mov_b32_e32 v121, 0
	v_mov_b32_e32 v122, 0
	v_mov_b32_e32 v123, 0
	v_mov_b32_e32 v124, 0
	v_mov_b32_e32 v125, 0
	v_mov_b32_e32 v126, 0
	v_mov_b32_e32 v127, 0
	s_mov_b32 s98, 0
.Lrg_grp_gu0s:
	ds_read_b128 v[128:131], v240
	ds_read_b128 v[132:135], v240 offset:2048
	ds_read_b128 v[136:139], v242
	ds_read_b128 v[140:143], v242 offset:2048
	ds_read_b128 v[144:147], v242 offset:4096
	ds_read_b128 v[148:151], v242 offset:6144
	s_cmp_eq_u32 s98, 0
	s_cbranch_scc1 .Lrg_first_gu0s
	v_mfma_f32_32x32x16_bf16 v[48:63], v[160:163], v[156:159], v[48:63]
	v_mfma_f32_32x32x16_bf16 v[96:111], v[164:167], v[152:155], v[96:111]
	v_mfma_f32_32x32x16_bf16 v[32:47], v[164:167], v[156:159], v[32:47]
	v_mfma_f32_32x32x16_bf16 v[80:95], v[168:171], v[152:155], v[80:95]
	v_mfma_f32_32x32x16_bf16 v[16:31], v[168:171], v[156:159], v[16:31]
	v_mfma_f32_32x32x16_bf16 v[64:79], v[172:175], v[152:155], v[64:79]
	v_mfma_f32_32x32x16_bf16 v[0:15], v[172:175], v[156:159], v[0:15]
.Lrg_first_gu0s:
	s_cmp_lt_u32 s101, 4096
	s_cbranch_scc0 .Lrg_ne_gu0s_0
	s_add_u32 vcc_lo, s99, 192
	v_add_u32_e32 v252, vcc_lo, v248
	s_add_u32 m0, s101, 98304
	v_add_u32_e32 v253, 262144, v252
	global_load_lds_dwordx4 v252, s[56:57]
	s_add_u32 m0, s101, 106496
	s_add_u32 vcc_lo, s100, 192
	global_load_lds_dwordx4 v253, s[56:57]
	v_add_u32_e32 v254, vcc_lo, v248
	s_add_u32 m0, s101, 114688
	v_add_u32_e32 v255, 262144, v254
	global_load_lds_dwordx4 v254, s[58:59]
	s_add_u32 m0, s101, 122880
	s_nop 0
	global_load_lds_dwordx4 v255, s[58:59]
.Lrg_ne_gu0s_0:
	s_waitcnt lgkmcnt(0)
	v_mfma_f32_32x32x16_bf16 v[112:127], v[136:139], v[128:131], v[112:127]
	ds_read_b128 v[152:155], v241
	ds_read_b128 v[156:159], v241 offset:2048
	ds_read_b128 v[160:163], v243
	ds_read_b128 v[164:167], v243 offset:2048
	ds_read_b128 v[168:171], v243 offset:4096
	ds_read_b128 v[172:175], v243 offset:6144
	v_mfma_f32_32x32x16_bf16 v[48:63], v[136:139], v[132:135], v[48:63]
	v_mfma_f32_32x32x16_bf16 v[96:111], v[140:143], v[128:131], v[96:111]
	v_mfma_f32_32x32x16_bf16 v[32:47], v[140:143], v[132:135], v[32:47]
	v_mfma_f32_32x32x16_bf16 v[80:95], v[144:147], v[128:131], v[80:95]
	v_mfma_f32_32x32x16_bf16 v[16:31], v[144:147], v[132:135], v[16:31]
	v_mfma_f32_32x32x16_bf16 v[64:79], v[148:151], v[128:131], v[64:79]
	v_mfma_f32_32x32x16_bf16 v[0:15], v[148:151], v[132:135], v[0:15]
	s_cmp_lt_u32 s101, 4096
	s_cbranch_scc1 .Lrg_nl_gu0s_0
	s_add_u32 vcc_lo, s99, 192
	v_add_u32_e32 v252, vcc_lo, v248
	s_add_u32 m0, s101, 98304
	v_add_u32_e32 v253, 262144, v252
	global_load_lds_dwordx4 v252, s[56:57]
	s_add_u32 m0, s101, 106496
	s_add_u32 vcc_lo, s100, 192
	global_load_lds_dwordx4 v253, s[56:57]
	v_add_u32_e32 v254, vcc_lo, v248
	s_add_u32 m0, s101, 114688
	v_add_u32_e32 v255, 262144, v254
	global_load_lds_dwordx4 v254, s[58:59]
	s_add_u32 m0, s101, 122880
	s_nop 0
	global_load_lds_dwordx4 v255, s[58:59]
.Lrg_nl_gu0s_0:
	s_cmp_eq_u32 s98, 7
	s_cbranch_scc0 .Lrg_nosw_gu0s
	s_add_u32 vcc_lo, s55, 1
	s_sub_u32 vcc_hi, s30, 1
	s_min_u32 vcc_lo, vcc_lo, vcc_hi
	s_lshl_b32 vcc_lo, vcc_lo, 3
	s_and_b32 vcc_hi, s10, 7
	s_add_u32 vcc_lo, vcc_lo, vcc_hi
	s_lshr_b32 s99, s10, 3
	s_cmp_lt_u32 vcc_lo, 90
	s_cbranch_scc0 .Lrg_gu2_1
	s_mul_i32 vcc_hi, vcc_lo, 0xcccd
	s_lshr_b32 vcc_hi, vcc_hi, 18
	s_mul_i32 m0, vcc_hi, 5
	s_sub_u32 m0, vcc_lo, m0
	s_lshl_b32 vcc_hi, vcc_hi, 3
	s_lshr_b32 vcc_lo, s99, 2
	s_add_u32 vcc_lo, vcc_lo, vcc_hi
	s_and_b32 vcc_hi, s99, 3
	s_lshl_b32 m0, m0, 2
	s_add_u32 vcc_hi, vcc_hi, m0
	s_branch .Lrg_gud_1

.Lrg_gud_1:
	s_lshl_b32 s99, vcc_lo, 19
	s_lshl_b32 s100, vcc_hi, 19
	s_sub_u32 s99, s99, 256
	s_sub_u32 s100, s100, 256
	s_mov_b32 vcc_hi, 0
.Lrg_nosw_gu0s:
	s_waitcnt lgkmcnt(0)
	v_mfma_f32_32x32x16_bf16 v[112:127], v[160:163], v[152:155], v[112:127]
	s_waitcnt vmcnt(8)
	s_barrier
	ds_read_b128 v[128:131], v240 offset:32768
	ds_read_b128 v[132:135], v240 offset:34816
	ds_read_b128 v[136:139], v242 offset:32768
	ds_read_b128 v[140:143], v242 offset:34816
	ds_read_b128 v[144:147], v242 offset:36864
	ds_read_b128 v[148:151], v242 offset:38912
	v_mfma_f32_32x32x16_bf16 v[48:63], v[160:163], v[156:159], v[48:63]
	v_mfma_f32_32x32x16_bf16 v[96:111], v[164:167], v[152:155], v[96:111]
	v_mfma_f32_32x32x16_bf16 v[32:47], v[164:167], v[156:159], v[32:47]
	v_mfma_f32_32x32x16_bf16 v[80:95], v[168:171], v[152:155], v[80:95]
	v_mfma_f32_32x32x16_bf16 v[16:31], v[168:171], v[156:159], v[16:31]
	v_mfma_f32_32x32x16_bf16 v[64:79], v[172:175], v[152:155], v[64:79]
	v_mfma_f32_32x32x16_bf16 v[0:15], v[172:175], v[156:159], v[0:15]
	s_cmp_lt_u32 s101, 4096
	s_cbranch_scc0 .Lrg_ne_gu0s_1
	s_add_u32 vcc_lo, s99, 256
	v_add_u32_e32 v252, vcc_lo, v248
	s_add_u32 m0, s101, 0
	v_add_u32_e32 v253, 262144, v252
	global_load_lds_dwordx4 v252, s[56:57]
	s_add_u32 m0, s101, 8192
	s_add_u32 vcc_lo, s100, 256
	global_load_lds_dwordx4 v253, s[56:57]
	v_add_u32_e32 v254, vcc_lo, v248
	s_add_u32 m0, s101, 16384
	v_add_u32_e32 v255, 262144, v254
	global_load_lds_dwordx4 v254, s[58:59]
	s_add_u32 m0, s101, 24576
	s_nop 0
	global_load_lds_dwordx4 v255, s[58:59]
.Lrg_ne_gu0s_1:
	s_waitcnt lgkmcnt(0)
	v_mfma_f32_32x32x16_bf16 v[112:127], v[136:139], v[128:131], v[112:127]
	ds_read_b128 v[152:155], v241 offset:32768
	ds_read_b128 v[156:159], v241 offset:34816
	ds_read_b128 v[160:163], v243 offset:32768
	ds_read_b128 v[164:167], v243 offset:34816
	ds_read_b128 v[168:171], v243 offset:36864
	ds_read_b128 v[172:175], v243 offset:38912
	v_mfma_f32_32x32x16_bf16 v[48:63], v[136:139], v[132:135], v[48:63]
	v_mfma_f32_32x32x16_bf16 v[96:111], v[140:143], v[128:131], v[96:111]
	v_mfma_f32_32x32x16_bf16 v[32:47], v[140:143], v[132:135], v[32:47]
	v_mfma_f32_32x32x16_bf16 v[80:95], v[144:147], v[128:131], v[80:95]
	v_mfma_f32_32x32x16_bf16 v[16:31], v[144:147], v[132:135], v[16:31]
	v_mfma_f32_32x32x16_bf16 v[64:79], v[148:151], v[128:131], v[64:79]
	v_mfma_f32_32x32x16_bf16 v[0:15], v[148:151], v[132:135], v[0:15]
	s_cmp_lt_u32 s101, 4096
	s_cbranch_scc1 .Lrg_nl_gu0s_1
	s_add_u32 vcc_lo, s99, 256
	v_add_u32_e32 v252, vcc_lo, v248
	s_add_u32 m0, s101, 0
	v_add_u32_e32 v253, 262144, v252
	global_load_lds_dwordx4 v252, s[56:57]
	s_add_u32 m0, s101, 8192
	s_add_u32 vcc_lo, s100, 256
	global_load_lds_dwordx4 v253, s[56:57]
	v_add_u32_e32 v254, vcc_lo, v248
	s_add_u32 m0, s101, 16384
	v_add_u32_e32 v255, 262144, v254
	global_load_lds_dwordx4 v254, s[58:59]
	s_add_u32 m0, s101, 24576
	s_nop 0
	global_load_lds_dwordx4 v255, s[58:59]
.Lrg_nl_gu0s_1:
	s_waitcnt lgkmcnt(0)
	v_mfma_f32_32x32x16_bf16 v[112:127], v[160:163], v[152:155], v[112:127]
	s_waitcnt vmcnt(8)
	s_barrier
	ds_read_b128 v[128:131], v244
	ds_read_b128 v[132:135], v244 offset:2048
	ds_read_b128 v[136:139], v246
	ds_read_b128 v[140:143], v246 offset:2048
	ds_read_b128 v[144:147], v246 offset:4096
	ds_read_b128 v[148:151], v246 offset:6144
	v_mfma_f32_32x32x16_bf16 v[48:63], v[160:163], v[156:159], v[48:63]
	v_mfma_f32_32x32x16_bf16 v[96:111], v[164:167], v[152:155], v[96:111]
	v_mfma_f32_32x32x16_bf16 v[32:47], v[164:167], v[156:159], v[32:47]
	v_mfma_f32_32x32x16_bf16 v[80:95], v[168:171], v[152:155], v[80:95]
	v_mfma_f32_32x32x16_bf16 v[16:31], v[168:171], v[156:159], v[16:31]
	v_mfma_f32_32x32x16_bf16 v[64:79], v[172:175], v[152:155], v[64:79]
	v_mfma_f32_32x32x16_bf16 v[0:15], v[172:175], v[156:159], v[0:15]
	s_cmp_lt_u32 s101, 4096
	s_cbranch_scc0 .Lrg_ne_gu0s_2
	s_add_u32 vcc_lo, s99, 320
	v_add_u32_e32 v252, vcc_lo, v248
	s_add_u32 m0, s101, 32768
	v_add_u32_e32 v253, 262144, v252
	global_load_lds_dwordx4 v252, s[56:57]
	s_add_u32 m0, s101, 40960
	s_add_u32 vcc_lo, s100, 320
	global_load_lds_dwordx4 v253, s[56:57]
	v_add_u32_e32 v254, vcc_lo, v248
	s_add_u32 m0, s101, 49152
	v_add_u32_e32 v255, 262144, v254
	global_load_lds_dwordx4 v254, s[58:59]
	s_add_u32 m0, s101, 57344
	s_nop 0
	global_load_lds_dwordx4 v255, s[58:59]
.Lrg_ne_gu0s_2:
	s_waitcnt lgkmcnt(0)
	v_mfma_f32_32x32x16_bf16 v[112:127], v[136:139], v[128:131], v[112:127]
	ds_read_b128 v[152:155], v245
	ds_read_b128 v[156:159], v245 offset:2048
	ds_read_b128 v[160:163], v247
	ds_read_b128 v[164:167], v247 offset:2048
	ds_read_b128 v[168:171], v247 offset:4096
	ds_read_b128 v[172:175], v247 offset:6144
	v_mfma_f32_32x32x16_bf16 v[48:63], v[136:139], v[132:135], v[48:63]
	v_mfma_f32_32x32x16_bf16 v[96:111], v[140:143], v[128:131], v[96:111]
	v_mfma_f32_32x32x16_bf16 v[32:47], v[140:143], v[132:135], v[32:47]
	v_mfma_f32_32x32x16_bf16 v[80:95], v[144:147], v[128:131], v[80:95]
	v_mfma_f32_32x32x16_bf16 v[16:31], v[144:147], v[132:135], v[16:31]
	v_mfma_f32_32x32x16_bf16 v[64:79], v[148:151], v[128:131], v[64:79]
	v_mfma_f32_32x32x16_bf16 v[0:15], v[148:151], v[132:135], v[0:15]
	s_cmp_lt_u32 s101, 4096
	s_cbranch_scc1 .Lrg_nl_gu0s_2
	s_add_u32 vcc_lo, s99, 320
	v_add_u32_e32 v252, vcc_lo, v248
	s_add_u32 m0, s101, 32768
	v_add_u32_e32 v253, 262144, v252
	global_load_lds_dwordx4 v252, s[56:57]
	s_add_u32 m0, s101, 40960
	s_add_u32 vcc_lo, s100, 320
	global_load_lds_dwordx4 v253, s[56:57]
	v_add_u32_e32 v254, vcc_lo, v248
	s_add_u32 m0, s101, 49152
	v_add_u32_e32 v255, 262144, v254
	global_load_lds_dwordx4 v254, s[58:59]
	s_add_u32 m0, s101, 57344
	s_nop 0
	global_load_lds_dwordx4 v255, s[58:59]
.Lrg_nl_gu0s_2:
	s_waitcnt lgkmcnt(0)
	v_mfma_f32_32x32x16_bf16 v[112:127], v[160:163], v[152:155], v[112:127]
	s_waitcnt vmcnt(8)
	s_barrier
	ds_read_b128 v[128:131], v244 offset:32768
	ds_read_b128 v[132:135], v244 offset:34816
	ds_read_b128 v[136:139], v246 offset:32768
	ds_read_b128 v[140:143], v246 offset:34816
	ds_read_b128 v[144:147], v246 offset:36864
	ds_read_b128 v[148:151], v246 offset:38912
	v_mfma_f32_32x32x16_bf16 v[48:63], v[160:163], v[156:159], v[48:63]
	v_mfma_f32_32x32x16_bf16 v[96:111], v[164:167], v[152:155], v[96:111]
	v_mfma_f32_32x32x16_bf16 v[32:47], v[164:167], v[156:159], v[32:47]
	v_mfma_f32_32x32x16_bf16 v[80:95], v[168:171], v[152:155], v[80:95]
	v_mfma_f32_32x32x16_bf16 v[16:31], v[168:171], v[156:159], v[16:31]
	v_mfma_f32_32x32x16_bf16 v[64:79], v[172:175], v[152:155], v[64:79]
	v_mfma_f32_32x32x16_bf16 v[0:15], v[172:175], v[156:159], v[0:15]
	s_cmp_lt_u32 s101, 4096
	s_cbranch_scc0 .Lrg_ne_gu0s_3
	s_cmp_eq_u32 s98, 7
	s_cbranch_scc1 .Lrg_ne_gu0s_3
	s_add_u32 vcc_lo, s99, 384
	v_add_u32_e32 v252, vcc_lo, v248
	s_add_u32 m0, s101, 65536
	v_add_u32_e32 v253, 262144, v252
	global_load_lds_dwordx4 v252, s[56:57]
	s_add_u32 m0, s101, 73728
	s_add_u32 vcc_lo, s100, 384
	global_load_lds_dwordx4 v253, s[56:57]
	v_add_u32_e32 v254, vcc_lo, v248
	s_add_u32 m0, s101, 81920
	v_add_u32_e32 v255, 262144, v254
	global_load_lds_dwordx4 v254, s[58:59]
	s_add_u32 m0, s101, 90112
	s_nop 0
	global_load_lds_dwordx4 v255, s[58:59]
.Lrg_ne_gu0s_3:
	s_waitcnt lgkmcnt(0)
	v_mfma_f32_32x32x16_bf16 v[112:127], v[136:139], v[128:131], v[112:127]
	ds_read_b128 v[152:155], v245 offset:32768
	ds_read_b128 v[156:159], v245 offset:34816
	ds_read_b128 v[160:163], v247 offset:32768
	ds_read_b128 v[164:167], v247 offset:34816
	ds_read_b128 v[168:171], v247 offset:36864
	ds_read_b128 v[172:175], v247 offset:38912
	v_mfma_f32_32x32x16_bf16 v[48:63], v[136:139], v[132:135], v[48:63]
	v_mfma_f32_32x32x16_bf16 v[96:111], v[140:143], v[128:131], v[96:111]
	v_mfma_f32_32x32x16_bf16 v[32:47], v[140:143], v[132:135], v[32:47]
	v_mfma_f32_32x32x16_bf16 v[80:95], v[144:147], v[128:131], v[80:95]
	v_mfma_f32_32x32x16_bf16 v[16:31], v[144:147], v[132:135], v[16:31]
	v_mfma_f32_32x32x16_bf16 v[64:79], v[148:151], v[128:131], v[64:79]
	v_mfma_f32_32x32x16_bf16 v[0:15], v[148:151], v[132:135], v[0:15]
	s_cmp_lt_u32 s101, 4096
	s_cbranch_scc1 .Lrg_nl_gu0s_3
	s_cmp_eq_u32 s98, 7
	s_cbranch_scc1 .Lrg_nl_gu0s_3
	s_add_u32 vcc_lo, s99, 384
	v_add_u32_e32 v252, vcc_lo, v248
	s_add_u32 m0, s101, 65536
	v_add_u32_e32 v253, 262144, v252
	global_load_lds_dwordx4 v252, s[56:57]
	s_add_u32 m0, s101, 73728
	s_add_u32 vcc_lo, s100, 384
	global_load_lds_dwordx4 v253, s[56:57]
	v_add_u32_e32 v254, vcc_lo, v248
	s_add_u32 m0, s101, 81920
	v_add_u32_e32 v255, 262144, v254
	global_load_lds_dwordx4 v254, s[58:59]
	s_add_u32 m0, s101, 90112
	s_nop 0
	global_load_lds_dwordx4 v255, s[58:59]
.Lrg_nl_gu0s_3:
	s_waitcnt lgkmcnt(0)
	v_mfma_f32_32x32x16_bf16 v[112:127], v[160:163], v[152:155], v[112:127]
	s_cmp_eq_u32 s98, 7
	s_cbranch_scc1 .Lrg_w4_gu0s
	s_waitcnt vmcnt(8)
	s_branch .Lrg_wd_gu0s
.Lrg_w4_gu0s:
	s_waitcnt vmcnt(4)
.Lrg_wd_gu0s:
	s_barrier
	s_add_u32 s99, s99, 256
	s_add_u32 s100, s100, 256
	s_add_u32 s98, s98, 1
	s_cmp_lt_u32 s98, 8
	s_cbranch_scc1 .Lrg_grp_gu0s
	v_mfma_f32_32x32x16_bf16 v[48:63], v[160:163], v[156:159], v[48:63]
	v_mfma_f32_32x32x16_bf16 v[96:111], v[164:167], v[152:155], v[96:111]
	v_mfma_f32_32x32x16_bf16 v[32:47], v[164:167], v[156:159], v[32:47]
	v_mfma_f32_32x32x16_bf16 v[80:95], v[168:171], v[152:155], v[80:95]
	v_mfma_f32_32x32x16_bf16 v[16:31], v[168:171], v[156:159], v[16:31]
	v_mfma_f32_32x32x16_bf16 v[64:79], v[172:175], v[152:155], v[64:79]
	v_mfma_f32_32x32x16_bf16 v[0:15], v[172:175], v[156:159], v[0:15]
	s_nop 15
	s_branch .LBB0_651

.LBB0_660:
	s_waitcnt vmcnt(0)
	v_readlane_b32 s62, v239, 60
	s_barrier
